# diet loop + P6 hook: first 16 gate loads issued before the first wait
# baseline (speedup 1.0000x reference)
; #define GAS __attribute__((address_space(1)))
; __device__ __forceinline__ float frcp(float x) { return __builtin_amdgcn_rcpf(x); }
; __device__ __forceinline__ void unpack8(u32x4 w, f32x4& a, f32x4& b) { a = (f32x4){bf_lo(w.x), bf_hi(w.x), bf_lo(w.y), bf_hi(w.y)}; b = (f32x4){bf_lo(w.z), bf_hi(w.z), bf_lo(w.w), bf_hi(w.w)}; }
;     __device__ __forceinline__ void hook(f32x4 (&acc)[2][2][4][2], const Unit& u, int seg, int wr, int wc, int fr, int fq) const {
;         const GAS bf16_t* gbase = Pg + (size_t)(u.pm * 256 + wr * 64 + fr) * PW + PC_GATE + (seg - 1) * 1024 + u.pn * 256 + wc * 32 + 8 * fq;
; #pragma unroll
;         for (int ai = 0; ai < 2; ++ai) {
;             u32x4 ga[4][2], gb[4][2];
; #pragma unroll
;             for (int m = 0; m < 4; ++m)
; #pragma unroll
;                 for (int bj = 0; bj < 2; ++bj) { const GAS bf16_t* gp = gbase + (size_t)(ai * 128 + m * 16) * PW + bj * 128;
;                     ga[m][bj] = *(const GAS u32x4*)gp; gb[m][bj] = *(const GAS u32x4*)(gp + 1024); }
; #pragma unroll
;             for (int m = 0; m < 4; ++m)
; #pragma unroll
;                 for (int bj = 0; bj < 2; ++bj) { f32x4 a0, a1, b0, b1; unpack8(ga[m][bj], a0, a1); unpack8(gb[m][bj], b0, b1);
; #pragma unroll
;                     for (int i = 0; i < 4; ++i) { acc[ai][bj][m][0][i] *= a0[i] * frcp(b0[i]); acc[ai][bj][m][1][i] *= a1[i] * frcp(b1[i]); } }
;             asm volatile("" ::: "memory");
;         }
;     }
.LBB0_1027:
	s_andn2_b64 vcc, exec, s[52:53]
	s_cbranch_vccnz .LBB0_1029
	global_load_dwordx4 v[194:197], v[182:183], off offset:2048
	global_load_dwordx4 v[198:201], v[182:183], off
	global_load_dwordx4 v[202:205], v[182:183], off offset:2304
	global_load_dwordx4 v[206:209], v[182:183], off offset:256
	v_add_co_u32_e32 v128, vcc, 0x28000, v182
	s_nop 1
	v_addc_co_u32_e32 v129, vcc, 0, v183, vcc
	global_load_dwordx4 v[210:213], v[128:129], off
	global_load_dwordx4 v[160:163], v[128:129], off offset:256
	global_load_dwordx4 v[214:217], v[128:129], off offset:2048
	global_load_dwordx4 v[218:221], v[128:129], off offset:2304
	v_add_co_u32_e32 v130, vcc, s71, v182
	s_nop 1
	v_addc_co_u32_e32 v131, vcc, 0, v183, vcc
	global_load_dwordx4 v[152:155], v[130:131], off
	global_load_dwordx4 v[144:147], v[130:131], off offset:256
	global_load_dwordx4 v[156:159], v[130:131], off offset:2048
	global_load_dwordx4 v[148:151], v[130:131], off offset:2304
	v_add_co_u32_e32 v132, vcc, s72, v182
	s_nop 1
	v_addc_co_u32_e32 v133, vcc, 0, v183, vcc
	global_load_dwordx4 v[136:139], v[132:133], off
	global_load_dwordx4 v[128:131], v[132:133], off offset:256
	global_load_dwordx4 v[140:143], v[132:133], off offset:2048
	s_nop 0
	global_load_dwordx4 v[132:135], v[132:133], off offset:2304
	s_waitcnt vmcnt(0)
	v_lshlrev_b32_e32 v193, 16, v194
	v_and_b32_e32 v223, 0xffff0000, v194
	v_lshlrev_b32_e32 v234, 16, v203
	v_and_b32_e32 v235, 0xffff0000, v203
	v_rcp_f32_e32 v222, v193
	v_rcp_f32_e32 v223, v223
	v_rcp_f32_e32 v234, v234
	v_rcp_f32_e32 v235, v235
	v_lshlrev_b32_e32 v236, 16, v205
	v_and_b32_e32 v237, 0xffff0000, v205
	v_lshlrev_b32_e32 v226, 16, v195
	v_and_b32_e32 v227, 0xffff0000, v195
	v_lshlrev_b32_e32 v194, 16, v198
	v_and_b32_e32 v195, 0xffff0000, v198
	v_rcp_f32_e32 v236, v236
	v_rcp_f32_e32 v237, v237
	v_lshlrev_b32_e32 v224, 16, v196
	v_and_b32_e32 v225, 0xffff0000, v196
	v_lshlrev_b32_e32 v230, 16, v202
	v_and_b32_e32 v231, 0xffff0000, v202
	v_lshlrev_b32_e32 v202, 16, v206
	v_and_b32_e32 v203, 0xffff0000, v206
	v_lshlrev_b32_e32 v206, 16, v207
	v_pk_mul_f32 v[194:195], v[222:223], v[194:195]
	v_and_b32_e32 v207, 0xffff0000, v207
	v_rcp_f32_e32 v224, v224
	v_rcp_f32_e32 v225, v225
	v_pk_mul_f32 v[120:121], v[120:121], v[194:195]
	v_pk_mul_f32 v[194:195], v[234:235], v[206:207]
	v_rcp_f32_e32 v226, v226
	v_pk_mul_f32 v[118:119], v[118:119], v[194:195]
	v_lshlrev_b32_e32 v194, 16, v209
	v_and_b32_e32 v195, 0xffff0000, v209
	v_rcp_f32_e32 v227, v227
	v_pk_mul_f32 v[194:195], v[236:237], v[194:195]
	v_lshlrev_b32_e32 v228, 16, v197
	v_and_b32_e32 v229, 0xffff0000, v197
	v_lshlrev_b32_e32 v196, 16, v200
	v_and_b32_e32 v197, 0xffff0000, v200
	v_pk_mul_f32 v[114:115], v[114:115], v[194:195]
	v_pk_mul_f32 v[196:197], v[224:225], v[196:197]
	v_lshlrev_b32_e32 v198, 16, v199
	v_and_b32_e32 v199, 0xffff0000, v199
	v_rcp_f32_e32 v228, v228
	v_rcp_f32_e32 v229, v229
	v_pk_mul_f32 v[124:125], v[124:125], v[196:197]
	v_pk_mul_f32 v[198:199], v[226:227], v[198:199]
	v_rcp_f32_e32 v230, v230
	v_rcp_f32_e32 v231, v231
	v_pk_mul_f32 v[122:123], v[122:123], v[198:199]
	v_lshlrev_b32_e32 v200, 16, v201
	v_and_b32_e32 v201, 0xffff0000, v201
	v_pk_mul_f32 v[200:201], v[228:229], v[200:201]
	v_pk_mul_f32 v[202:203], v[230:231], v[202:203]
	v_pk_mul_f32 v[126:127], v[126:127], v[200:201]
	v_pk_mul_f32 v[116:117], v[116:117], v[202:203]
	v_lshlrev_b32_e32 v232, 16, v204
	v_and_b32_e32 v233, 0xffff0000, v204
	v_rcp_f32_e32 v232, v232
	v_rcp_f32_e32 v233, v233
	v_lshlrev_b32_e32 v204, 16, v208
	v_and_b32_e32 v205, 0xffff0000, v208
	v_pk_mul_f32 v[204:205], v[232:233], v[204:205]
	s_nop 0
	v_pk_mul_f32 v[112:113], v[112:113], v[204:205]
	s_waitcnt vmcnt(0)
	v_lshlrev_b32_e32 v198, 16, v210
	v_and_b32_e32 v199, 0xffff0000, v210
	v_lshlrev_b32_e32 v193, 16, v214
	v_and_b32_e32 v195, 0xffff0000, v214
	v_rcp_f32_e32 v194, v193
	v_rcp_f32_e32 v195, v195
	v_lshlrev_b32_e32 v196, 16, v216
	v_and_b32_e32 v197, 0xffff0000, v216
	v_rcp_f32_e32 v196, v196
	v_rcp_f32_e32 v197, v197
	v_pk_mul_f32 v[194:195], v[194:195], v[198:199]
	v_lshlrev_b32_e32 v200, 16, v215
	v_pk_mul_f32 v[108:109], v[108:109], v[194:195]
	v_lshlrev_b32_e32 v194, 16, v212
	v_and_b32_e32 v195, 0xffff0000, v212
	v_and_b32_e32 v201, 0xffff0000, v215
	v_pk_mul_f32 v[194:195], v[196:197], v[194:195]
	v_lshlrev_b32_e32 v202, 16, v217
	v_pk_mul_f32 v[104:105], v[104:105], v[194:195]
	v_rcp_f32_e32 v194, v200
	v_rcp_f32_e32 v195, v201
	v_and_b32_e32 v203, 0xffff0000, v217
	v_rcp_f32_e32 v196, v202
	v_rcp_f32_e32 v197, v203
	v_lshlrev_b32_e32 v198, 16, v211
	v_and_b32_e32 v199, 0xffff0000, v211
	v_pk_mul_f32 v[194:195], v[194:195], v[198:199]
	v_lshlrev_b32_e32 v193, 16, v218
	v_pk_mul_f32 v[110:111], v[110:111], v[194:195]
	v_lshlrev_b32_e32 v194, 16, v213
	v_and_b32_e32 v195, 0xffff0000, v213
	v_pk_mul_f32 v[194:195], v[196:197], v[194:195]
	v_lshlrev_b32_e32 v196, 16, v220
	v_pk_mul_f32 v[106:107], v[106:107], v[194:195]
	v_and_b32_e32 v195, 0xffff0000, v218
	v_rcp_f32_e32 v194, v193
	v_rcp_f32_e32 v195, v195
	v_and_b32_e32 v197, 0xffff0000, v220
	v_rcp_f32_e32 v196, v196
	v_rcp_f32_e32 v197, v197
	v_lshlrev_b32_e32 v198, 16, v160
	v_and_b32_e32 v199, 0xffff0000, v160
	v_pk_mul_f32 v[194:195], v[194:195], v[198:199]
	v_lshlrev_b32_e32 v202, 16, v221
	v_and_b32_e32 v203, 0xffff0000, v221
	v_pk_mul_f32 v[100:101], v[100:101], v[194:195]
	v_lshlrev_b32_e32 v194, 16, v162
	v_and_b32_e32 v195, 0xffff0000, v162
	v_pk_mul_f32 v[194:195], v[196:197], v[194:195]
	v_rcp_f32_e32 v160, v202
	v_lshlrev_b32_e32 v196, 16, v161
	v_and_b32_e32 v197, 0xffff0000, v161
	v_rcp_f32_e32 v161, v203
	v_lshlrev_b32_e32 v200, 16, v219
; #define GAS __attribute__((address_space(1)))
; __device__ __forceinline__ float frcp(float x) { return __builtin_amdgcn_rcpf(x); }
; __device__ __forceinline__ void unpack8(u32x4 w, f32x4& a, f32x4& b) { a = (f32x4){bf_lo(w.x), bf_hi(w.x), bf_lo(w.y), bf_hi(w.y)}; b = (f32x4){bf_lo(w.z), bf_hi(w.z), bf_lo(w.w), bf_hi(w.w)}; }
;     __device__ __forceinline__ void hook(f32x4 (&acc)[2][2][4][2], const Unit& u, int seg, int wr, int wc, int fr, int fq) const {
;     ...
;                 for (int bj = 0; bj < 2; ++bj) { const GAS bf16_t* gp = gbase + (size_t)(ai * 128 + m * 16) * PW + bj * 128;
;                     ga[m][bj] = *(const GAS u32x4*)gp; gb[m][bj] = *(const GAS u32x4*)(gp + 1024); }
; #pragma unroll
;             for (int m = 0; m < 4; ++m)
; #pragma unroll
;                 for (int bj = 0; bj < 2; ++bj) { f32x4 a0, a1, b0, b1; unpack8(ga[m][bj], a0, a1); unpack8(gb[m][bj], b0, b1);
; #pragma unroll
;                     for (int i = 0; i < 4; ++i) { acc[ai][bj][m][0][i] *= a0[i] * frcp(b0[i]); acc[ai][bj][m][1][i] *= a1[i] * frcp(b1[i]); } }
	v_and_b32_e32 v201, 0xffff0000, v219
	v_pk_mul_f32 v[96:97], v[96:97], v[194:195]
	v_rcp_f32_e32 v194, v200
	v_rcp_f32_e32 v195, v201
	v_lshlrev_b32_e32 v162, 16, v163
	v_and_b32_e32 v163, 0xffff0000, v163
	v_pk_mul_f32 v[160:161], v[160:161], v[162:163]
	v_pk_mul_f32 v[194:195], v[194:195], v[196:197]
	v_pk_mul_f32 v[98:99], v[98:99], v[160:161]
	v_lshlrev_b32_e32 v160, 16, v156
	v_and_b32_e32 v161, 0xffff0000, v156
	v_lshlrev_b32_e32 v162, 16, v157
	v_and_b32_e32 v163, 0xffff0000, v157
	v_rcp_f32_e32 v156, v160
	v_rcp_f32_e32 v157, v161
	v_pk_mul_f32 v[102:103], v[102:103], v[194:195]
	v_lshlrev_b32_e32 v193, 16, v158
	v_and_b32_e32 v194, 0xffff0000, v158
	v_lshlrev_b32_e32 v195, 16, v159
	v_and_b32_e32 v196, 0xffff0000, v159
	v_rcp_f32_e32 v158, v193
	v_rcp_f32_e32 v159, v194
	v_lshlrev_b32_e32 v160, 16, v152
	v_and_b32_e32 v161, 0xffff0000, v152
	v_pk_mul_f32 v[156:157], v[156:157], v[160:161]
	v_rcp_f32_e32 v152, v195
	v_pk_mul_f32 v[92:93], v[92:93], v[156:157]
	v_lshlrev_b32_e32 v156, 16, v154
	v_and_b32_e32 v157, 0xffff0000, v154
	v_pk_mul_f32 v[156:157], v[158:159], v[156:157]
	v_lshlrev_b32_e32 v158, 16, v153
	v_and_b32_e32 v159, 0xffff0000, v153
	v_rcp_f32_e32 v153, v196
	v_pk_mul_f32 v[88:89], v[88:89], v[156:157]
	v_rcp_f32_e32 v156, v162
	v_rcp_f32_e32 v157, v163
	v_lshlrev_b32_e32 v154, 16, v155
	v_and_b32_e32 v155, 0xffff0000, v155
	v_pk_mul_f32 v[152:153], v[152:153], v[154:155]
	v_pk_mul_f32 v[156:157], v[156:157], v[158:159]
	v_pk_mul_f32 v[90:91], v[90:91], v[152:153]
	v_lshlrev_b32_e32 v152, 16, v148
	v_and_b32_e32 v153, 0xffff0000, v148
	v_lshlrev_b32_e32 v154, 16, v149
	v_and_b32_e32 v155, 0xffff0000, v149
	v_rcp_f32_e32 v148, v152
	v_rcp_f32_e32 v149, v153
	v_pk_mul_f32 v[94:95], v[94:95], v[156:157]
	v_lshlrev_b32_e32 v156, 16, v150
	v_and_b32_e32 v157, 0xffff0000, v150
	v_lshlrev_b32_e32 v158, 16, v151
	v_and_b32_e32 v159, 0xffff0000, v151
	v_rcp_f32_e32 v150, v156
	v_rcp_f32_e32 v151, v157
	v_lshlrev_b32_e32 v152, 16, v144
	v_and_b32_e32 v153, 0xffff0000, v144
	v_pk_mul_f32 v[148:149], v[148:149], v[152:153]
	v_rcp_f32_e32 v144, v158
	v_pk_mul_f32 v[84:85], v[84:85], v[148:149]
	v_lshlrev_b32_e32 v148, 16, v146
	v_and_b32_e32 v149, 0xffff0000, v146
	v_pk_mul_f32 v[148:149], v[150:151], v[148:149]
	v_lshlrev_b32_e32 v150, 16, v145
	v_and_b32_e32 v151, 0xffff0000, v145
	v_rcp_f32_e32 v145, v159
	v_lshlrev_b32_e32 v146, 16, v147
	v_and_b32_e32 v147, 0xffff0000, v147
	v_pk_mul_f32 v[80:81], v[80:81], v[148:149]
	v_pk_mul_f32 v[144:145], v[144:145], v[146:147]
	v_add_co_u32_e32 v146, vcc, s73, v182
	v_rcp_f32_e32 v148, v154
	s_nop 0
	v_addc_co_u32_e32 v147, vcc, 0, v183, vcc
	v_rcp_f32_e32 v149, v155
	global_load_dwordx4 v[156:159], v[146:147], off offset:2048
	global_load_dwordx4 v[194:197], v[146:147], off offset:2304
	global_load_dwordx4 v[160:163], v[146:147], off
	global_load_dwordx4 v[198:201], v[146:147], off offset:256
	v_pk_mul_f32 v[148:149], v[148:149], v[150:151]
	v_pk_mul_f32 v[82:83], v[82:83], v[144:145]
	v_pk_mul_f32 v[86:87], v[86:87], v[148:149]
	v_lshlrev_b32_e32 v144, 16, v140
	v_and_b32_e32 v145, 0xffff0000, v140
	v_lshlrev_b32_e32 v148, 16, v141
	v_and_b32_e32 v149, 0xffff0000, v141
	v_lshlrev_b32_e32 v141, 16, v142
	v_and_b32_e32 v150, 0xffff0000, v142
	v_rcp_f32_e32 v140, v144
	v_rcp_f32_e32 v142, v141
	v_rcp_f32_e32 v141, v145
	v_lshlrev_b32_e32 v151, 16, v143
	v_and_b32_e32 v152, 0xffff0000, v143
	v_rcp_f32_e32 v143, v150
	v_lshlrev_b32_e32 v144, 16, v136
	v_and_b32_e32 v145, 0xffff0000, v136
	v_pk_mul_f32 v[140:141], v[140:141], v[144:145]
	v_rcp_f32_e32 v136, v151
	v_pk_mul_f32 v[76:77], v[76:77], v[140:141]
	v_lshlrev_b32_e32 v140, 16, v138
	v_and_b32_e32 v141, 0xffff0000, v138
	v_pk_mul_f32 v[140:141], v[142:143], v[140:141]
	v_lshlrev_b32_e32 v142, 16, v137
	v_and_b32_e32 v143, 0xffff0000, v137
	v_rcp_f32_e32 v137, v152
	v_pk_mul_f32 v[72:73], v[72:73], v[140:141]
	v_rcp_f32_e32 v140, v148
	v_rcp_f32_e32 v141, v149
	v_lshlrev_b32_e32 v138, 16, v139
	v_and_b32_e32 v139, 0xffff0000, v139
	v_pk_mul_f32 v[136:137], v[136:137], v[138:139]
	v_pk_mul_f32 v[140:141], v[140:141], v[142:143]
	v_pk_mul_f32 v[74:75], v[74:75], v[136:137]
	v_lshlrev_b32_e32 v136, 16, v132
	v_and_b32_e32 v137, 0xffff0000, v132
	v_lshlrev_b32_e32 v138, 16, v133
	v_and_b32_e32 v139, 0xffff0000, v133
	v_rcp_f32_e32 v132, v136
	v_rcp_f32_e32 v133, v137
	v_pk_mul_f32 v[78:79], v[78:79], v[140:141]
	v_lshlrev_b32_e32 v140, 16, v134
	v_and_b32_e32 v141, 0xffff0000, v134
	v_lshlrev_b32_e32 v142, 16, v135
	v_and_b32_e32 v143, 0xffff0000, v135
	v_rcp_f32_e32 v134, v140
	v_rcp_f32_e32 v135, v141
	v_lshlrev_b32_e32 v136, 16, v128
	v_and_b32_e32 v137, 0xffff0000, v128
	v_pk_mul_f32 v[132:133], v[132:133], v[136:137]
	v_rcp_f32_e32 v128, v142
	v_pk_mul_f32 v[68:69], v[68:69], v[132:133]
	v_lshlrev_b32_e32 v132, 16, v130
	v_and_b32_e32 v133, 0xffff0000, v130
	v_pk_mul_f32 v[132:133], v[134:135], v[132:133]
	v_lshlrev_b32_e32 v134, 16, v129
	v_and_b32_e32 v135, 0xffff0000, v129
	v_rcp_f32_e32 v129, v143
	v_lshlrev_b32_e32 v130, 16, v131
	v_and_b32_e32 v131, 0xffff0000, v131
	v_pk_mul_f32 v[64:65], v[64:65], v[132:133]
	v_pk_mul_f32 v[128:129], v[128:129], v[130:131]
	v_rcp_f32_e32 v132, v138
	v_pk_mul_f32 v[66:67], v[66:67], v[128:129]
	v_add_co_u32_e32 v128, vcc, s74, v182
	v_rcp_f32_e32 v133, v139
	s_nop 0
	v_addc_co_u32_e32 v129, vcc, 0, v183, vcc
	global_load_dwordx4 v[202:205], v[128:129], off
	global_load_dwordx4 v[206:209], v[128:129], off offset:256
	global_load_dwordx4 v[210:213], v[128:129], off offset:2048
	global_load_dwordx4 v[214:217], v[128:129], off offset:2304
	v_add_co_u32_e32 v128, vcc, s75, v182
	v_pk_mul_f32 v[132:133], v[132:133], v[134:135]
	s_nop 0
	v_addc_co_u32_e32 v129, vcc, 0, v183, vcc
	global_load_dwordx4 v[152:155], v[128:129], off
	global_load_dwordx4 v[144:147], v[128:129], off offset:256
	global_load_dwordx4 v[218:221], v[128:129], off offset:2048
	global_load_dwordx4 v[148:151], v[128:129], off offset:2304
	s_waitcnt vmcnt(0)
; #define GAS __attribute__((address_space(1)))
; __device__ __forceinline__ float frcp(float x) { return __builtin_amdgcn_rcpf(x); }
; __device__ __forceinline__ void unpack8(u32x4 w, f32x4& a, f32x4& b) { a = (f32x4){bf_lo(w.x), bf_hi(w.x), bf_lo(w.y), bf_hi(w.y)}; b = (f32x4){bf_lo(w.z), bf_hi(w.z), bf_lo(w.w), bf_hi(w.w)}; }
;     __device__ __forceinline__ void hook(f32x4 (&acc)[2][2][4][2], const Unit& u, int seg, int wr, int wc, int fr, int fq) const {
;     ...
;                 for (int bj = 0; bj < 2; ++bj) { const GAS bf16_t* gp = gbase + (size_t)(ai * 128 + m * 16) * PW + bj * 128;
;                     ga[m][bj] = *(const GAS u32x4*)gp; gb[m][bj] = *(const GAS u32x4*)(gp + 1024); }
; #pragma unroll
;             for (int m = 0; m < 4; ++m)
; #pragma unroll
;                 for (int bj = 0; bj < 2; ++bj) { f32x4 a0, a1, b0, b1; unpack8(ga[m][bj], a0, a1); unpack8(gb[m][bj], b0, b1);
; #pragma unroll
;                     for (int i = 0; i < 4; ++i) { acc[ai][bj][m][0][i] *= a0[i] * frcp(b0[i]); acc[ai][bj][m][1][i] *= a1[i] * frcp(b1[i]); } }
	v_lshlrev_b32_e32 v193, 16, v156
	v_and_b32_e32 v222, 0xffff0000, v156
	v_lshlrev_b32_e32 v224, 16, v157
	v_and_b32_e32 v225, 0xffff0000, v157
	v_rcp_f32_e32 v156, v193
	v_rcp_f32_e32 v157, v222
	v_lshlrev_b32_e32 v223, 16, v158
	v_and_b32_e32 v226, 0xffff0000, v158
	v_pk_mul_f32 v[70:71], v[70:71], v[132:133]
	v_add_co_u32_e32 v132, vcc, s76, v182
	v_lshlrev_b32_e32 v227, 16, v159
	v_and_b32_e32 v228, 0xffff0000, v159
	v_rcp_f32_e32 v158, v223
	v_rcp_f32_e32 v159, v226
	v_addc_co_u32_e32 v133, vcc, 0, v183, vcc
	v_lshlrev_b32_e32 v222, 16, v160
	v_and_b32_e32 v223, 0xffff0000, v160
	global_load_dwordx4 v[136:139], v[132:133], off
	global_load_dwordx4 v[128:131], v[132:133], off offset:256
	global_load_dwordx4 v[140:143], v[132:133], off offset:2048
	s_nop 0
	global_load_dwordx4 v[132:135], v[132:133], off offset:2304
	v_pk_mul_f32 v[156:157], v[156:157], v[222:223]
	v_lshlrev_b32_e32 v160, 16, v161
	v_pk_mul_f32 v[60:61], v[60:61], v[156:157]
	v_lshlrev_b32_e32 v156, 16, v162
	v_and_b32_e32 v157, 0xffff0000, v162
	v_pk_mul_f32 v[156:157], v[158:159], v[156:157]
	v_rcp_f32_e32 v158, v227
	v_pk_mul_f32 v[56:57], v[56:57], v[156:157]
	v_rcp_f32_e32 v156, v224
	v_rcp_f32_e32 v157, v225
	v_rcp_f32_e32 v159, v228
	v_and_b32_e32 v161, 0xffff0000, v161
	v_lshlrev_b32_e32 v162, 16, v195
	v_pk_mul_f32 v[156:157], v[156:157], v[160:161]
	v_lshlrev_b32_e32 v160, 16, v198
	v_pk_mul_f32 v[62:63], v[62:63], v[156:157]
	v_lshlrev_b32_e32 v156, 16, v163
	v_and_b32_e32 v157, 0xffff0000, v163
	v_pk_mul_f32 v[156:157], v[158:159], v[156:157]
	v_lshlrev_b32_e32 v158, 16, v196
	v_pk_mul_f32 v[58:59], v[58:59], v[156:157]
	v_lshlrev_b32_e32 v156, 16, v194
	v_and_b32_e32 v157, 0xffff0000, v194
	v_rcp_f32_e32 v156, v156
	v_rcp_f32_e32 v157, v157
	v_and_b32_e32 v159, 0xffff0000, v196
	v_rcp_f32_e32 v158, v158
	v_rcp_f32_e32 v159, v159
	v_and_b32_e32 v161, 0xffff0000, v198
	v_pk_mul_f32 v[156:157], v[156:157], v[160:161]
	v_and_b32_e32 v163, 0xffff0000, v195
	v_pk_mul_f32 v[52:53], v[52:53], v[156:157]
	v_lshlrev_b32_e32 v156, 16, v200
	v_and_b32_e32 v157, 0xffff0000, v200
	v_pk_mul_f32 v[156:157], v[158:159], v[156:157]
	v_lshlrev_b32_e32 v193, 16, v197
	v_pk_mul_f32 v[48:49], v[48:49], v[156:157]
	v_rcp_f32_e32 v156, v162
	v_rcp_f32_e32 v157, v163
	v_and_b32_e32 v194, 0xffff0000, v197
	v_rcp_f32_e32 v158, v193
	v_rcp_f32_e32 v159, v194
	v_lshlrev_b32_e32 v160, 16, v199
	v_and_b32_e32 v161, 0xffff0000, v199
	v_pk_mul_f32 v[156:157], v[156:157], v[160:161]
	s_waitcnt vmcnt(0)
	v_lshlrev_b32_e32 v160, 16, v202
	v_pk_mul_f32 v[54:55], v[54:55], v[156:157]
	v_lshlrev_b32_e32 v156, 16, v201
	v_and_b32_e32 v157, 0xffff0000, v201
	v_pk_mul_f32 v[156:157], v[158:159], v[156:157]
	v_lshlrev_b32_e32 v158, 16, v212
	v_pk_mul_f32 v[50:51], v[50:51], v[156:157]
	v_lshlrev_b32_e32 v156, 16, v210
	v_and_b32_e32 v157, 0xffff0000, v210
	v_rcp_f32_e32 v156, v156
	v_rcp_f32_e32 v157, v157
	v_and_b32_e32 v159, 0xffff0000, v212
	v_rcp_f32_e32 v158, v158
	v_rcp_f32_e32 v159, v159
	v_and_b32_e32 v161, 0xffff0000, v202
	v_pk_mul_f32 v[156:157], v[156:157], v[160:161]
	v_lshlrev_b32_e32 v162, 16, v211
	v_pk_mul_f32 v[44:45], v[44:45], v[156:157]
	v_lshlrev_b32_e32 v156, 16, v204
	v_and_b32_e32 v157, 0xffff0000, v204
	v_and_b32_e32 v163, 0xffff0000, v211
	v_pk_mul_f32 v[156:157], v[158:159], v[156:157]
	v_lshlrev_b32_e32 v193, 16, v213
	v_pk_mul_f32 v[40:41], v[40:41], v[156:157]
	v_rcp_f32_e32 v156, v162
	v_rcp_f32_e32 v157, v163
	v_and_b32_e32 v194, 0xffff0000, v213
	v_rcp_f32_e32 v158, v193
	v_rcp_f32_e32 v159, v194
	v_lshlrev_b32_e32 v160, 16, v203
	v_and_b32_e32 v161, 0xffff0000, v203
	v_pk_mul_f32 v[156:157], v[156:157], v[160:161]
	v_lshlrev_b32_e32 v160, 16, v206
	v_pk_mul_f32 v[46:47], v[46:47], v[156:157]
	v_lshlrev_b32_e32 v156, 16, v205
	v_and_b32_e32 v157, 0xffff0000, v205
	v_pk_mul_f32 v[156:157], v[158:159], v[156:157]
	v_lshlrev_b32_e32 v158, 16, v216
	v_pk_mul_f32 v[42:43], v[42:43], v[156:157]
	v_lshlrev_b32_e32 v156, 16, v214
	v_and_b32_e32 v157, 0xffff0000, v214
	v_rcp_f32_e32 v156, v156
	v_rcp_f32_e32 v157, v157
	v_and_b32_e32 v159, 0xffff0000, v216
	v_rcp_f32_e32 v158, v158
	v_rcp_f32_e32 v159, v159
	v_and_b32_e32 v161, 0xffff0000, v206
	v_pk_mul_f32 v[156:157], v[156:157], v[160:161]
	v_lshlrev_b32_e32 v162, 16, v215
	v_pk_mul_f32 v[36:37], v[36:37], v[156:157]
	v_lshlrev_b32_e32 v156, 16, v208
	v_and_b32_e32 v157, 0xffff0000, v208
	v_and_b32_e32 v163, 0xffff0000, v215
	v_pk_mul_f32 v[156:157], v[158:159], v[156:157]
	v_lshlrev_b32_e32 v193, 16, v217
	v_pk_mul_f32 v[32:33], v[32:33], v[156:157]
	v_rcp_f32_e32 v156, v162
	v_rcp_f32_e32 v157, v163
	v_and_b32_e32 v194, 0xffff0000, v217
	v_rcp_f32_e32 v158, v193
	v_rcp_f32_e32 v159, v194
	v_lshlrev_b32_e32 v160, 16, v207
	v_and_b32_e32 v161, 0xffff0000, v207
	v_pk_mul_f32 v[156:157], v[156:157], v[160:161]
; __device__ __forceinline__ float frcp(float x) { return __builtin_amdgcn_rcpf(x); }
; __device__ __forceinline__ void unpack8(u32x4 w, f32x4& a, f32x4& b) { a = (f32x4){bf_lo(w.x), bf_hi(w.x), bf_lo(w.y), bf_hi(w.y)}; b = (f32x4){bf_lo(w.z), bf_hi(w.z), bf_lo(w.w), bf_hi(w.w)}; }
;     __device__ __forceinline__ void hook(f32x4 (&acc)[2][2][4][2], const Unit& u, int seg, int wr, int wc, int fr, int fq) const {
;     ...
;                 for (int bj = 0; bj < 2; ++bj) { f32x4 a0, a1, b0, b1; unpack8(ga[m][bj], a0, a1); unpack8(gb[m][bj], b0, b1);
; #pragma unroll
;                     for (int i = 0; i < 4; ++i) { acc[ai][bj][m][0][i] *= a0[i] * frcp(b0[i]); acc[ai][bj][m][1][i] *= a1[i] * frcp(b1[i]); } }
	v_lshlrev_b32_e32 v160, 16, v152
	v_pk_mul_f32 v[38:39], v[38:39], v[156:157]
	v_lshlrev_b32_e32 v156, 16, v209
	v_and_b32_e32 v157, 0xffff0000, v209
	v_pk_mul_f32 v[156:157], v[158:159], v[156:157]
	v_lshlrev_b32_e32 v158, 16, v220
	v_pk_mul_f32 v[34:35], v[34:35], v[156:157]
	v_lshlrev_b32_e32 v156, 16, v218
	v_and_b32_e32 v157, 0xffff0000, v218
	v_rcp_f32_e32 v156, v156
	v_rcp_f32_e32 v157, v157
	v_and_b32_e32 v159, 0xffff0000, v220
	v_rcp_f32_e32 v158, v158
	v_rcp_f32_e32 v159, v159
	v_and_b32_e32 v161, 0xffff0000, v152
	v_pk_mul_f32 v[156:157], v[156:157], v[160:161]
	v_lshlrev_b32_e32 v193, 16, v221
	v_and_b32_e32 v194, 0xffff0000, v221
	v_pk_mul_f32 v[28:29], v[28:29], v[156:157]
	v_lshlrev_b32_e32 v156, 16, v154
	v_and_b32_e32 v157, 0xffff0000, v154
	v_pk_mul_f32 v[156:157], v[158:159], v[156:157]
	v_rcp_f32_e32 v152, v193
	v_lshlrev_b32_e32 v158, 16, v153
	v_and_b32_e32 v159, 0xffff0000, v153
	v_rcp_f32_e32 v153, v194
	v_lshlrev_b32_e32 v162, 16, v219
	v_and_b32_e32 v163, 0xffff0000, v219
	v_pk_mul_f32 v[24:25], v[24:25], v[156:157]
	v_rcp_f32_e32 v156, v162
	v_rcp_f32_e32 v157, v163
	v_lshlrev_b32_e32 v154, 16, v155
	v_and_b32_e32 v155, 0xffff0000, v155
	v_pk_mul_f32 v[152:153], v[152:153], v[154:155]
	v_pk_mul_f32 v[156:157], v[156:157], v[158:159]
	v_pk_mul_f32 v[26:27], v[26:27], v[152:153]
	v_lshlrev_b32_e32 v152, 16, v148
	v_and_b32_e32 v153, 0xffff0000, v148
	v_lshlrev_b32_e32 v154, 16, v149
	v_and_b32_e32 v155, 0xffff0000, v149
	v_rcp_f32_e32 v148, v152
	v_rcp_f32_e32 v149, v153
	v_pk_mul_f32 v[30:31], v[30:31], v[156:157]
	v_lshlrev_b32_e32 v156, 16, v150
	v_and_b32_e32 v157, 0xffff0000, v150
	v_lshlrev_b32_e32 v158, 16, v151
	v_and_b32_e32 v159, 0xffff0000, v151
	v_rcp_f32_e32 v150, v156
	v_rcp_f32_e32 v151, v157
	v_lshlrev_b32_e32 v152, 16, v144
	v_and_b32_e32 v153, 0xffff0000, v144
	v_pk_mul_f32 v[148:149], v[148:149], v[152:153]
	v_rcp_f32_e32 v144, v158
	v_pk_mul_f32 v[20:21], v[20:21], v[148:149]
	v_lshlrev_b32_e32 v148, 16, v146
	v_and_b32_e32 v149, 0xffff0000, v146
	v_pk_mul_f32 v[148:149], v[150:151], v[148:149]
	v_lshlrev_b32_e32 v150, 16, v145
	v_and_b32_e32 v151, 0xffff0000, v145
	v_rcp_f32_e32 v145, v159
	v_pk_mul_f32 v[16:17], v[16:17], v[148:149]
	v_rcp_f32_e32 v148, v154
	v_rcp_f32_e32 v149, v155
	v_lshlrev_b32_e32 v146, 16, v147
	v_and_b32_e32 v147, 0xffff0000, v147
	v_pk_mul_f32 v[144:145], v[144:145], v[146:147]
	v_pk_mul_f32 v[148:149], v[148:149], v[150:151]
	v_pk_mul_f32 v[18:19], v[18:19], v[144:145]
	s_waitcnt vmcnt(0)
	v_lshlrev_b32_e32 v144, 16, v140
	v_and_b32_e32 v145, 0xffff0000, v140
	v_lshlrev_b32_e32 v146, 16, v141
	v_and_b32_e32 v147, 0xffff0000, v141
	v_rcp_f32_e32 v140, v144
	v_rcp_f32_e32 v141, v145
	v_pk_mul_f32 v[22:23], v[22:23], v[148:149]
	v_lshlrev_b32_e32 v148, 16, v142
	v_and_b32_e32 v149, 0xffff0000, v142
	v_lshlrev_b32_e32 v150, 16, v143
	v_and_b32_e32 v151, 0xffff0000, v143
	v_rcp_f32_e32 v142, v148
	v_rcp_f32_e32 v143, v149
	v_lshlrev_b32_e32 v144, 16, v136
	v_and_b32_e32 v145, 0xffff0000, v136
	v_pk_mul_f32 v[140:141], v[140:141], v[144:145]
	v_rcp_f32_e32 v136, v150
	v_pk_mul_f32 v[12:13], v[12:13], v[140:141]
	v_lshlrev_b32_e32 v140, 16, v138
	v_and_b32_e32 v141, 0xffff0000, v138
	v_pk_mul_f32 v[140:141], v[142:143], v[140:141]
	v_lshlrev_b32_e32 v142, 16, v137
	v_and_b32_e32 v143, 0xffff0000, v137
	v_rcp_f32_e32 v137, v151
	v_pk_mul_f32 v[8:9], v[8:9], v[140:141]
	v_rcp_f32_e32 v140, v146
	v_rcp_f32_e32 v141, v147
	v_lshlrev_b32_e32 v138, 16, v139
	v_and_b32_e32 v139, 0xffff0000, v139
	v_pk_mul_f32 v[136:137], v[136:137], v[138:139]
	v_pk_mul_f32 v[140:141], v[140:141], v[142:143]
	v_pk_mul_f32 v[10:11], v[10:11], v[136:137]
	v_lshlrev_b32_e32 v136, 16, v132
	v_and_b32_e32 v137, 0xffff0000, v132
	v_lshlrev_b32_e32 v138, 16, v133
	v_and_b32_e32 v139, 0xffff0000, v133
	v_rcp_f32_e32 v132, v136
	v_rcp_f32_e32 v133, v137
	v_pk_mul_f32 v[14:15], v[14:15], v[140:141]
	v_lshlrev_b32_e32 v140, 16, v134
	v_and_b32_e32 v141, 0xffff0000, v134
	v_lshlrev_b32_e32 v142, 16, v135
	v_and_b32_e32 v143, 0xffff0000, v135
	v_rcp_f32_e32 v134, v140
	v_rcp_f32_e32 v135, v141
	v_lshlrev_b32_e32 v136, 16, v128
	v_and_b32_e32 v137, 0xffff0000, v128
	v_pk_mul_f32 v[132:133], v[132:133], v[136:137]
	v_rcp_f32_e32 v128, v142
	v_pk_mul_f32 v[4:5], v[4:5], v[132:133]
	v_lshlrev_b32_e32 v132, 16, v130
	v_and_b32_e32 v133, 0xffff0000, v130
	v_pk_mul_f32 v[132:133], v[134:135], v[132:133]
	v_lshlrev_b32_e32 v134, 16, v129
	v_pk_mul_f32 v[0:1], v[0:1], v[132:133]
	v_rcp_f32_e32 v132, v138
	v_rcp_f32_e32 v133, v139
	v_and_b32_e32 v135, 0xffff0000, v129
	v_rcp_f32_e32 v129, v143
	v_lshlrev_b32_e32 v130, 16, v131
	v_and_b32_e32 v131, 0xffff0000, v131
	v_pk_mul_f32 v[132:133], v[132:133], v[134:135]
	v_pk_mul_f32 v[128:129], v[128:129], v[130:131]
	v_pk_mul_f32 v[6:7], v[6:7], v[132:133]
	v_pk_mul_f32 v[2:3], v[2:3], v[128:129]
